# adaLN GEMV mods 5-8 moved to P5b idle WGs (column-owner, in-WG reduce); P0: GEMV-owning waves skip transposes
# speedup vs baseline: 1.0062x; 1.0062x over previous
.LBB0_19:
	s_lshr_b32 s20, s64, 6
	s_lshl_b32 s0, s73, 3
	s_add_i32 s96, s0, s20
	v_readlane_b32 s0, v241, 0
	s_lshl_b32 s86, s0, 3
	v_readlane_b32 s1, v241, 1
	s_add_u32 s0, s94, 0x100000
	s_addc_u32 s1, s95, 0
	s_add_u32 s30, s94, 0x400000
	s_addc_u32 s31, s95, 0
	s_add_u32 s28, s94, 0x3000000
	s_addc_u32 s29, s95, 0
	s_add_u32 s74, s94, 0x4600000
	s_addc_u32 s75, s95, 0
	s_add_u32 s2, s94, 0x6200000
	v_writelane_b32 v241, s2, 53
	s_addc_u32 s2, s95, 0
	s_cmp_lt_i32 s90, 1
	v_writelane_b32 v241, s2, 54
	s_cselect_b64 s[2:3], -1, 0
	s_cmp_gt_i32 s91, 0
	s_cselect_b64 s[4:5], -1, 0
	s_and_b64 s[2:3], s[2:3], s[4:5]
	s_andn2_b64 vcc, exec, s[2:3]
	v_and_b32_e32 v147, 63, v146
	s_cbranch_vccnz .LBB0_41
	s_cmpk_gt_i32 s96, 0x27f
	s_cbranch_scc1 .LBB0_25
	v_readlane_b32 s4, v241, 5
	v_readlane_b32 s6, v241, 7
	v_readlane_b32 s10, v241, 11
	v_lshlrev_b32_e32 v2, 2, v147
	v_readlane_b32 s7, v241, 8
	v_readlane_b32 s11, v241, 12
	v_readlane_b32 s12, v241, 13
	v_readlane_b32 s13, v241, 14
	v_readlane_b32 s14, v241, 15
	v_readlane_b32 s15, v241, 16
	v_readlane_b32 s16, v241, 17
	v_readlane_b32 s17, v241, 18
	v_readlane_b32 s18, v241, 19
	v_readlane_b32 s19, v241, 20
	s_add_u32 s10, s6, 28
	v_mov_b32_e32 v7, 0
	s_addc_u32 s11, s7, 0
	s_mov_b32 s12, 0x12000
	v_lshlrev_b32_e32 v6, 2, v2
	s_mov_b32 s13, 0x24000
	s_mov_b32 s14, 0x36000
	s_mov_b32 s15, 0x48000
	s_mov_b32 s16, 0x5a000
	s_mov_b32 s17, 0x6c000
	s_mov_b32 s18, 0x7e000
	s_mov_b32 s19, s96
	v_readlane_b32 s5, v241, 6
	v_readlane_b32 s8, v241, 9
	v_readlane_b32 s9, v241, 10
.LBB0_22:
	s_mul_hi_i32 s4, s19, 0x66666667
	s_lshr_b32 s5, s4, 31
	s_ashr_i32 s22, s4, 4
	s_add_i32 s22, s22, s5
	s_mul_i32 s4, s22, 0x28
	s_lshl_b32 s6, s22, 7
	v_readlane_b32 s36, v241, 5
	s_sub_i32 s4, s19, s4
	s_ashr_i32 s7, s6, 31
	s_mul_i32 s5, s22, 0x900000
	v_readlane_b32 s40, v241, 9
	s_mul_hi_i32 s8, s6, 0x12000
	v_readlane_b32 s41, v241, 10
	s_add_u32 s9, s40, s5
	s_addc_u32 s23, s41, s8
	s_lshl_b32 s4, s4, 8
	s_ashr_i32 s5, s4, 31
	s_lshl_b64 s[4:5], s[4:5], 2
	s_add_u32 s8, s9, s4
	s_addc_u32 s9, s23, s5
	s_lshl_b64 s[6:7], s[6:7], 2
	s_add_u32 s6, s10, s6
	v_lshl_add_u64 v[8:9], s[8:9], 0, v[6:7]
	s_addc_u32 s7, s11, s7
	s_mov_b64 s[8:9], 0
	v_mov_b32_e32 v2, 0
	v_mov_b32_e32 v3, v7
	v_mov_b32_e32 v4, 0
	v_mov_b32_e32 v5, v7
	v_readlane_b32 s37, v241, 6
	v_readlane_b32 s38, v241, 7
	v_readlane_b32 s39, v241, 8
	v_readlane_b32 s42, v241, 11
	v_readlane_b32 s43, v241, 12
	v_readlane_b32 s44, v241, 13
	v_readlane_b32 s45, v241, 14
	v_readlane_b32 s46, v241, 15
	v_readlane_b32 s47, v241, 16
	v_readlane_b32 s48, v241, 17
	v_readlane_b32 s49, v241, 18
	v_readlane_b32 s50, v241, 19
	v_readlane_b32 s51, v241, 20
.LBB0_23:
	global_load_dwordx4 v[10:13], v7, s[6:7] offset:-28
	global_load_dwordx4 v[14:17], v7, s[6:7] offset:-12
	v_lshl_add_u64 v[22:23], v[8:9], 0, s[8:9]
	v_add_co_u32_e32 v24, vcc, s12, v22
	global_load_dwordx4 v[18:21], v[22:23], off nt
	s_nop 0
	v_addc_co_u32_e32 v25, vcc, 0, v23, vcc
	v_add_co_u32_e32 v26, vcc, s13, v22
	s_add_u32 s6, s6, 32
	s_nop 0
	v_addc_co_u32_e32 v27, vcc, 0, v23, vcc
	v_add_co_u32_e32 v30, vcc, s14, v22
	s_addc_u32 s7, s7, 0
	s_nop 0
	v_addc_co_u32_e32 v31, vcc, 0, v23, vcc
	v_add_co_u32_e32 v34, vcc, s15, v22
	s_add_u32 s8, s8, 0x90000
	s_nop 0
	v_addc_co_u32_e32 v35, vcc, 0, v23, vcc
	v_add_co_u32_e32 v38, vcc, s16, v22
	s_addc_u32 s9, s9, 0
	s_nop 0
	v_addc_co_u32_e32 v39, vcc, 0, v23, vcc
	v_add_co_u32_e32 v42, vcc, s17, v22
	s_cmp_eq_u32 s8, 0x900000
	s_nop 0
	v_addc_co_u32_e32 v43, vcc, 0, v23, vcc
	v_add_co_u32_e32 v46, vcc, s18, v22
	s_waitcnt vmcnt(2)
	v_mul_f32_e32 v1, 0xbfb8aa3b, v10
	v_addc_co_u32_e32 v47, vcc, 0, v23, vcc
	global_load_dwordx4 v[22:25], v[24:25], off nt
	s_nop 0
	global_load_dwordx4 v[26:29], v[26:27], off nt
	s_nop 0
	global_load_dwordx4 v[30:33], v[30:31], off nt
	s_nop 0
	global_load_dwordx4 v[34:37], v[34:35], off nt
	s_nop 0
	global_load_dwordx4 v[38:41], v[38:39], off nt
	s_nop 0
	global_load_dwordx4 v[42:45], v[42:43], off nt
	s_nop 0
	global_load_dwordx4 v[46:49], v[46:47], off nt
	v_mul_f32_e32 v50, 0xbfb8aa3b, v11
	v_exp_f32_e32 v1, v1
	v_mul_f32_e32 v51, 0xbfb8aa3b, v12
	v_exp_f32_e32 v50, v50
	v_mul_f32_e32 v52, 0xbfb8aa3b, v13
	v_exp_f32_e32 v51, v51
	s_waitcnt vmcnt(8)
	v_mul_f32_e32 v53, 0xbfb8aa3b, v14
	v_exp_f32_e32 v52, v52
	v_mul_f32_e32 v54, 0xbfb8aa3b, v15
	v_exp_f32_e32 v53, v53
	v_add_f32_e32 v1, 1.0, v1
	v_mul_f32_e32 v55, 0xbfb8aa3b, v16
	v_exp_f32_e32 v54, v54
	v_add_f32_e32 v50, 1.0, v50
	v_rcp_f32_e32 v1, v1
	v_mul_f32_e32 v56, 0xbfb8aa3b, v17
	v_exp_f32_e32 v55, v55
	v_add_f32_e32 v51, 1.0, v51
	v_rcp_f32_e32 v50, v50
	v_exp_f32_e32 v56, v56
	v_add_f32_e32 v52, 1.0, v52
	v_rcp_f32_e32 v51, v51
	v_add_f32_e32 v53, 1.0, v53
	v_rcp_f32_e32 v52, v52
	v_add_f32_e32 v54, 1.0, v54
	v_rcp_f32_e32 v53, v53
	v_mul_f32_e32 v10, v10, v1
	v_add_f32_e32 v55, 1.0, v55
	v_rcp_f32_e32 v54, v54
	v_mul_f32_e32 v50, v11, v50
	s_waitcnt vmcnt(7)
	v_pk_fma_f32 v[4:5], v[20:21], v[10:11], v[4:5] op_sel_hi:[1,0,1]
	v_pk_fma_f32 v[2:3], v[18:19], v[10:11], v[2:3] op_sel_hi:[1,0,1]
	v_add_f32_e32 v56, 1.0, v56
	v_rcp_f32_e32 v55, v55
	v_mul_f32_e32 v12, v12, v51
	v_rcp_f32_e32 v56, v56
	v_mul_f32_e32 v52, v13, v52
	v_mul_f32_e32 v14, v14, v53
	v_mul_f32_e32 v54, v15, v54
	v_mul_f32_e32 v16, v16, v55
	v_mul_f32_e32 v56, v17, v56
	s_waitcnt vmcnt(6)
	v_pk_fma_f32 v[4:5], v[24:25], v[50:51], v[4:5] op_sel_hi:[1,0,1]
	v_pk_fma_f32 v[2:3], v[22:23], v[50:51], v[2:3] op_sel_hi:[1,0,1]
	s_waitcnt vmcnt(5)
	v_pk_fma_f32 v[4:5], v[28:29], v[12:13], v[4:5] op_sel_hi:[1,0,1]
	v_pk_fma_f32 v[2:3], v[26:27], v[12:13], v[2:3] op_sel_hi:[1,0,1]
	s_waitcnt vmcnt(4)
	v_pk_fma_f32 v[4:5], v[32:33], v[52:53], v[4:5] op_sel_hi:[1,0,1]
	v_pk_fma_f32 v[2:3], v[30:31], v[52:53], v[2:3] op_sel_hi:[1,0,1]
	s_waitcnt vmcnt(3)
	v_pk_fma_f32 v[4:5], v[36:37], v[14:15], v[4:5] op_sel_hi:[1,0,1]
	v_pk_fma_f32 v[2:3], v[34:35], v[14:15], v[2:3] op_sel_hi:[1,0,1]
	s_waitcnt vmcnt(2)
	v_pk_fma_f32 v[4:5], v[40:41], v[54:55], v[4:5] op_sel_hi:[1,0,1]
	v_pk_fma_f32 v[2:3], v[38:39], v[54:55], v[2:3] op_sel_hi:[1,0,1]
	s_waitcnt vmcnt(1)
	v_pk_fma_f32 v[4:5], v[44:45], v[16:17], v[4:5] op_sel_hi:[1,0,1]
	v_pk_fma_f32 v[2:3], v[42:43], v[16:17], v[2:3] op_sel_hi:[1,0,1]
	s_waitcnt vmcnt(0)
	v_pk_fma_f32 v[4:5], v[48:49], v[56:57], v[4:5] op_sel_hi:[1,0,1]
	v_pk_fma_f32 v[2:3], v[46:47], v[56:57], v[2:3] op_sel_hi:[1,0,1]
	s_cbranch_scc0 .LBB0_23
	s_mul_hi_i32 s6, s22, 0x12000
	s_mul_i32 s22, s22, 0x12000
	s_add_u32 s7, s0, s22
	s_addc_u32 s6, s1, s6
	s_add_u32 s4, s7, s4
	s_addc_u32 s5, s6, s5
	s_add_i32 s19, s19, s86
	s_cmpk_gt_i32 s19, 0x27f
	global_store_dwordx4 v6, v[2:5], s[4:5]
	s_cbranch_scc0 .LBB0_22
.LBB0_25:
	v_readlane_b32 s4, v241, 0
	s_cmpk_eq_i32 s4, 0x100
	s_movk_i32 s4, 0x3000
	s_cselect_b32 s14, s4, 0x8200
	s_mov_b32 s98, s96
	s_mov_b32 s99, s86
	v_readlane_b32 s5, v241, 0
	s_nop 3
	s_cmpk_lg_i32 s5, 0x100
	s_cbranch_scc1 .Lp0bal_go
	s_sub_i32 s98, s96, 0x280
	s_cmp_lt_i32 s98, 0
	s_cbranch_scc1 .LBB0_40
	s_sub_i32 s99, s86, 0x280
.Lp0bal_go:
	s_cmp_ge_i32 s98, s14
	v_readlane_b32 s5, v241, 1
	s_cbranch_scc1 .LBB0_40
	s_lshl_b32 s4, s20, 14
	s_addk_i32 s4, 0x100
	v_lshrrev_b32_e32 v1, 5, v147
	v_and_b32_e32 v2, 31, v146
	v_lshlrev_b32_e32 v4, 3, v146
	v_lshl_add_u32 v7, v2, 2, s4
	v_mul_u32_u24_e32 v13, 0x84, v1
	v_lshrrev_b32_e32 v8, 3, v147
	v_and_b32_e32 v6, 56, v4
	v_mov_b32_e32 v3, 0
	v_mul_u32_u24_e32 v4, 0x84, v6
	v_lshlrev_b32_e32 v5, 2, v8
	v_add_u32_e32 v13, v7, v13
	v_add3_u32 v9, s4, v4, v5
	v_or_b32_e32 v10, 8, v8
	v_or_b32_e32 v11, 16, v8
	v_or_b32_e32 v12, 24, v8
	s_lshl_b32 s15, s98, 5
	s_lshl_b32 s16, s99, 5
	s_lshl_b32 s17, s98, 4
	s_lshl_b32 s18, s99, 4
	v_lshlrev_b32_e32 v4, 2, v2
	v_mov_b32_e32 v5, v3
	v_lshlrev_b32_e32 v6, 1, v6
	v_mov_b32_e32 v7, v3
	v_add_u32_e32 v14, 0x400, v13
	v_add_u32_e32 v15, 0x800, v13
	v_add_u32_e32 v16, 0xc00, v13
	v_add_u32_e32 v17, 0x1000, v13
	v_add_u32_e32 v18, 0x1400, v13
	v_add_u32_e32 v19, 0x1800, v13
	v_add_u32_e32 v20, 0x1c00, v13
	s_mov_b32 s19, s98
	s_branch .LBB0_28
.LBB0_27:
	v_mul_u32_u24_e32 v2, s10, v1
	v_lshlrev_b32_e32 v2, 2, v2
	v_lshl_add_u64 v[22:23], s[8:9], 0, v[2:3]
	v_lshl_add_u64 v[22:23], v[22:23], 0, v[4:5]
	s_lshl_b64 s[8:9], s[10:11], 3
	v_lshl_add_u64 v[24:25], v[22:23], 0, s[8:9]
	v_lshl_add_u64 v[26:27], v[24:25], 0, s[8:9]
	v_lshl_add_u64 v[28:29], v[26:27], 0, s[8:9]
	v_lshl_add_u64 v[30:31], v[28:29], 0, s[8:9]
	v_lshl_add_u64 v[32:33], v[30:31], 0, s[8:9]
	v_lshl_add_u64 v[34:35], v[32:33], 0, s[8:9]
	v_lshl_add_u64 v[36:37], v[34:35], 0, s[8:9]
	global_load_dword v2, v[22:23], off nt
	global_load_dword v21, v[24:25], off nt
	s_nop 0
	global_load_dword v24, v[26:27], off nt
	global_load_dword v25, v[28:29], off nt
	s_nop 0
	global_load_dword v26, v[30:31], off nt
	global_load_dword v27, v[32:33], off nt
	global_load_dword v28, v[34:35], off nt
	global_load_dword v29, v[36:37], off nt
	v_lshl_add_u64 v[22:23], v[36:37], 0, s[8:9]
	global_load_dword v30, v[22:23], off nt
	v_lshl_add_u64 v[22:23], v[22:23], 0, s[8:9]
	global_load_dword v31, v[22:23], off nt
	v_lshl_add_u64 v[22:23], v[22:23], 0, s[8:9]
	global_load_dword v32, v[22:23], off nt
	v_lshl_add_u64 v[22:23], v[22:23], 0, s[8:9]
	global_load_dword v33, v[22:23], off nt
	v_lshl_add_u64 v[22:23], v[22:23], 0, s[8:9]
	global_load_dword v34, v[22:23], off nt
	v_lshl_add_u64 v[22:23], v[22:23], 0, s[8:9]
	global_load_dword v35, v[22:23], off nt
	v_lshl_add_u64 v[22:23], v[22:23], 0, s[8:9]
	global_load_dword v36, v[22:23], off nt
	v_lshl_add_u64 v[22:23], v[22:23], 0, s[8:9]
	global_load_dword v37, v[22:23], off nt
	v_lshl_add_u64 v[22:23], v[22:23], 0, s[8:9]
	global_load_dword v38, v[22:23], off nt
	v_lshl_add_u64 v[22:23], v[22:23], 0, s[8:9]
	global_load_dword v39, v[22:23], off nt
	v_lshl_add_u64 v[22:23], v[22:23], 0, s[8:9]
	global_load_dword v40, v[22:23], off nt
	v_lshl_add_u64 v[22:23], v[22:23], 0, s[8:9]
	global_load_dword v41, v[22:23], off nt
	v_lshl_add_u64 v[22:23], v[22:23], 0, s[8:9]
	global_load_dword v42, v[22:23], off nt
	v_lshl_add_u64 v[22:23], v[22:23], 0, s[8:9]
	global_load_dword v43, v[22:23], off nt
	v_lshl_add_u64 v[22:23], v[22:23], 0, s[8:9]
	global_load_dword v44, v[22:23], off nt
	v_lshl_add_u64 v[22:23], v[22:23], 0, s[8:9]
	global_load_dword v45, v[22:23], off nt
	v_lshl_add_u64 v[22:23], v[22:23], 0, s[8:9]
	global_load_dword v46, v[22:23], off nt
	v_lshl_add_u64 v[22:23], v[22:23], 0, s[8:9]
	global_load_dword v47, v[22:23], off nt
	v_lshl_add_u64 v[22:23], v[22:23], 0, s[8:9]
	global_load_dword v48, v[22:23], off nt
	v_lshl_add_u64 v[22:23], v[22:23], 0, s[8:9]
	global_load_dword v49, v[22:23], off nt
	v_lshl_add_u64 v[22:23], v[22:23], 0, s[8:9]
	global_load_dword v50, v[22:23], off nt
	v_lshl_add_u64 v[22:23], v[22:23], 0, s[8:9]
	global_load_dword v51, v[22:23], off nt
	v_lshl_add_u64 v[22:23], v[22:23], 0, s[8:9]
	global_load_dword v52, v[22:23], off nt
	v_lshl_add_u64 v[22:23], v[22:23], 0, s[8:9]
	global_load_dword v22, v[22:23], off nt
	s_add_i32 s19, s19, s99
	s_add_i32 s15, s15, s16
	s_add_i32 s17, s17, s18
	s_cmp_lt_i32 s19, s14
	s_waitcnt vmcnt(30)
	ds_write2_b32 v13, v2, v21 offset1:66
	s_waitcnt vmcnt(28)
	ds_write2_b32 v13, v24, v25 offset0:132 offset1:198
	s_waitcnt vmcnt(26)
	ds_write2_b32 v14, v26, v27 offset0:8 offset1:74
	s_waitcnt vmcnt(24)
	ds_write2_b32 v14, v28, v29 offset0:140 offset1:206
	s_waitcnt vmcnt(22)
	ds_write2_b32 v15, v30, v31 offset0:16 offset1:82
	s_waitcnt vmcnt(20)
	ds_write2_b32 v15, v32, v33 offset0:148 offset1:214
	s_waitcnt vmcnt(18)
	ds_write2_b32 v16, v34, v35 offset0:24 offset1:90
	s_waitcnt vmcnt(16)
	ds_write2_b32 v16, v36, v37 offset0:156 offset1:222
	s_waitcnt vmcnt(14)
	ds_write2_b32 v17, v38, v39 offset0:32 offset1:98
	s_waitcnt vmcnt(12)
	ds_write2_b32 v17, v40, v41 offset0:164 offset1:230
	s_waitcnt vmcnt(10)
	ds_write2_b32 v18, v42, v43 offset0:40 offset1:106
	s_waitcnt vmcnt(8)
	ds_write2_b32 v18, v44, v45 offset0:172 offset1:238
	s_waitcnt vmcnt(6)
	ds_write2_b32 v19, v46, v47 offset0:48 offset1:114
	s_waitcnt vmcnt(4)
	ds_write2_b32 v19, v48, v49 offset0:180 offset1:246
	s_waitcnt vmcnt(2)
	ds_write2_b32 v20, v50, v51 offset0:56 offset1:122
	s_waitcnt vmcnt(0)
	ds_write2_b32 v20, v52, v22 offset0:188 offset1:254
	s_waitcnt lgkmcnt(0)
	ds_read2_b32 v[22:23], v9 offset1:33
	s_waitcnt lgkmcnt(0)
	v_cvt_pk_bf16_f32 v22, v22, v23
	ds_read2_b32 v[24:25], v9 offset0:66 offset1:99
	v_mul_u32_u24_e32 v2, s4, v8
	s_waitcnt lgkmcnt(0)
	v_cvt_pk_bf16_f32 v23, v24, v25
	ds_read2_b32 v[24:25], v9 offset0:132 offset1:165
	v_lshl_add_u64 v[28:29], s[6:7], 0, v[6:7]
	v_lshlrev_b32_e32 v2, 1, v2
	s_waitcnt lgkmcnt(0)
	v_cvt_pk_bf16_f32 v24, v24, v25
	ds_read2_b32 v[26:27], v9 offset0:198 offset1:231
	s_waitcnt lgkmcnt(0)
	v_cvt_pk_bf16_f32 v25, v26, v27
	v_lshl_add_u64 v[30:31], v[28:29], 0, v[2:3]
	ds_read2_b32 v[26:27], v9 offset0:8 offset1:41
	global_store_dwordx4 v[30:31], v[22:25], off
	v_mul_u32_u24_e32 v2, s4, v10
	v_lshlrev_b32_e32 v2, 1, v2
	s_waitcnt lgkmcnt(0)
	v_cvt_pk_bf16_f32 v22, v26, v27
	ds_read2_b32 v[24:25], v9 offset0:74 offset1:107
	s_waitcnt lgkmcnt(0)
	v_cvt_pk_bf16_f32 v23, v24, v25
	ds_read2_b32 v[24:25], v9 offset0:140 offset1:173
	s_waitcnt lgkmcnt(0)
	v_cvt_pk_bf16_f32 v24, v24, v25
	ds_read2_b32 v[26:27], v9 offset0:206 offset1:239
	s_waitcnt lgkmcnt(0)
	v_cvt_pk_bf16_f32 v25, v26, v27
	v_lshl_add_u64 v[30:31], v[28:29], 0, v[2:3]
	ds_read2_b32 v[26:27], v9 offset0:16 offset1:49
	global_store_dwordx4 v[30:31], v[22:25], off
	v_mul_u32_u24_e32 v2, s4, v11
	v_lshlrev_b32_e32 v2, 1, v2
	s_waitcnt lgkmcnt(0)
	v_cvt_pk_bf16_f32 v22, v26, v27
	ds_read2_b32 v[24:25], v9 offset0:82 offset1:115
	s_waitcnt lgkmcnt(0)
	v_cvt_pk_bf16_f32 v23, v24, v25
	ds_read2_b32 v[24:25], v9 offset0:148 offset1:181
	s_waitcnt lgkmcnt(0)
	v_cvt_pk_bf16_f32 v24, v24, v25
	ds_read2_b32 v[26:27], v9 offset0:214 offset1:247
	s_waitcnt lgkmcnt(0)
	v_cvt_pk_bf16_f32 v25, v26, v27
	v_lshl_add_u64 v[30:31], v[28:29], 0, v[2:3]
	v_mul_u32_u24_e32 v2, s4, v12
	ds_read2_b32 v[26:27], v9 offset0:24 offset1:57
	global_store_dwordx4 v[30:31], v[22:25], off
	v_lshlrev_b32_e32 v2, 1, v2
	v_lshl_add_u64 v[28:29], v[28:29], 0, v[2:3]
	s_waitcnt lgkmcnt(0)
	v_cvt_pk_bf16_f32 v22, v26, v27
	ds_read2_b32 v[24:25], v9 offset0:90 offset1:123
	s_waitcnt lgkmcnt(0)
	v_cvt_pk_bf16_f32 v23, v24, v25
	ds_read2_b32 v[24:25], v9 offset0:156 offset1:189
	s_waitcnt lgkmcnt(0)
	v_cvt_pk_bf16_f32 v24, v24, v25
	ds_read2_b32 v[26:27], v9 offset0:222 offset1:255
	s_waitcnt lgkmcnt(0)
	v_cvt_pk_bf16_f32 v25, v26, v27
	global_store_dwordx4 v[28:29], v[22:25], off
	s_waitcnt lgkmcnt(0)
	s_cbranch_scc0 .LBB0_40

.LBB0_95:
	s_cmp_lt_i32 s90, 2
	s_cselect_b64 s[2:3], -1, 0
	s_and_b64 s[2:3], s[2:3], s[4:5]
	s_andn2_b64 vcc, exec, s[2:3]
	s_cbranch_vccnz .LBB0_106
	v_lshl_add_u32 v1, s72, 9, v146
	s_movk_i32 s4, 0x9ff
	v_cmp_lt_i32_e32 vcc, s4, v1
	s_and_saveexec_b64 s[4:5], vcc
	s_xor_b64 s[4:5], exec, s[4:5]
	v_lshlrev_b32_e32 v64, 2, v146
	s_andn2_saveexec_b64 s[4:5], s[4:5]
	s_cbranch_execz .LBB0_102
	v_readlane_b32 s8, v241, 0
	s_add_u32 s6, s94, 0x300000
	v_readlane_b32 s9, v241, 1
	v_lshlrev_b32_e32 v64, 2, v146
	v_readlane_b32 s36, v241, 5
	s_addc_u32 s7, s95, 0
	s_lshl_b32 s10, s8, 9
	v_lshl_add_u32 v2, s72, 11, v64
	s_lshl_b32 s11, s8, 11
	s_mov_b64 s[8:9], 0
	s_mov_b32 s12, 0x48000
	s_mov_b32 s13, 0x5a000
	s_mov_b32 s14, 0x6c000
	s_mov_b32 s15, 0x7e000
	s_mov_b32 s16, 0x90000
	s_mov_b32 s17, 0xa2000
	s_mov_b32 s18, 0xb4000
	s_mov_b32 s19, 0xc6000
	s_mov_b32 s22, 0xd8000
	s_mov_b32 s23, 0xea000
	s_mov_b32 s24, 0xfc000
	s_mov_b32 s25, 0x10e000
	s_movk_i32 s26, 0x9ff
	v_readlane_b32 s42, v241, 11
	v_readlane_b32 s43, v241, 12
	v_readlane_b32 s37, v241, 6
	v_readlane_b32 s38, v241, 7
	v_readlane_b32 s39, v241, 8
	v_readlane_b32 s40, v241, 9
	v_readlane_b32 s41, v241, 10
	v_readlane_b32 s44, v241, 13
	v_readlane_b32 s45, v241, 14
	v_readlane_b32 s46, v241, 15
	v_readlane_b32 s47, v241, 16
	v_readlane_b32 s48, v241, 17
	v_readlane_b32 s49, v241, 18
	v_readlane_b32 s50, v241, 19
	v_readlane_b32 s51, v241, 20

.Lp5x_done:
	s_sub_i32 s0, s72, 0x80
	s_lshl_b32 s1, s0, 8
	s_add_u32 s1, s1, 0xa000
	v_lshrrev_b32_e32 v1, 4, v147
	v_and_b32_e32 v6, 15, v147
	v_lshl_add_u32 v1, s20, 8, v1
	v_mul_u32_u24_e32 v8, 0x12000, v1
	v_lshlrev_b32_e32 v6, 4, v6
	v_add3_u32 v8, v8, v6, s1
	v_mov_b32_e32 v9, 0
	v_readlane_b32 s4, v241, 9
	v_readlane_b32 s5, v241, 10
	s_nop 3
	v_lshl_add_u64 v[8:9], s[4:5], 0, v[8:9]
	v_lshlrev_b32_e32 v10, 2, v1
	v_mov_b32_e32 v11, 0
	v_readlane_b32 s6, v241, 7
	v_readlane_b32 s7, v241, 8
	s_nop 3
	v_lshl_add_u64 v[10:11], s[6:7], 0, v[10:11]
	s_mov_b32 s10, 0x48000
	s_mov_b32 s11, 0
	s_mov_b32 s12, 0x100
	s_mov_b32 s13, 0
	v_mov_b32_e32 v2, 0
	v_mov_b32_e32 v3, 0
	v_mov_b32_e32 v4, 0
	v_mov_b32_e32 v5, 0
	s_mov_b32 s8, 4
.Lg5_loop:
	global_load_dword v80, v[10:11], off offset:0
	global_load_dword v81, v[10:11], off offset:16
	global_load_dword v82, v[10:11], off offset:32
	global_load_dword v83, v[10:11], off offset:48
	global_load_dword v84, v[10:11], off offset:64
	global_load_dword v85, v[10:11], off offset:80
	global_load_dword v86, v[10:11], off offset:96
	global_load_dword v87, v[10:11], off offset:112
	global_load_dword v88, v[10:11], off offset:128
	global_load_dword v89, v[10:11], off offset:144
	global_load_dword v90, v[10:11], off offset:160
	global_load_dword v91, v[10:11], off offset:176
	global_load_dword v92, v[10:11], off offset:192
	global_load_dword v93, v[10:11], off offset:208
	global_load_dword v94, v[10:11], off offset:224
	global_load_dword v95, v[10:11], off offset:240
	v_lshl_add_u64 v[10:11], v[10:11], 0, s[12:13]
	global_load_dwordx4 v[16:19], v[8:9], off nt
	v_lshl_add_u64 v[8:9], v[8:9], 0, s[10:11]
	global_load_dwordx4 v[20:23], v[8:9], off nt
	v_lshl_add_u64 v[8:9], v[8:9], 0, s[10:11]
	global_load_dwordx4 v[24:27], v[8:9], off nt
	v_lshl_add_u64 v[8:9], v[8:9], 0, s[10:11]
	global_load_dwordx4 v[28:31], v[8:9], off nt
	v_lshl_add_u64 v[8:9], v[8:9], 0, s[10:11]
	global_load_dwordx4 v[32:35], v[8:9], off nt
	v_lshl_add_u64 v[8:9], v[8:9], 0, s[10:11]
	global_load_dwordx4 v[36:39], v[8:9], off nt
	v_lshl_add_u64 v[8:9], v[8:9], 0, s[10:11]
	global_load_dwordx4 v[40:43], v[8:9], off nt
	v_lshl_add_u64 v[8:9], v[8:9], 0, s[10:11]
	global_load_dwordx4 v[44:47], v[8:9], off nt
	v_lshl_add_u64 v[8:9], v[8:9], 0, s[10:11]
	global_load_dwordx4 v[48:51], v[8:9], off nt
	v_lshl_add_u64 v[8:9], v[8:9], 0, s[10:11]
	global_load_dwordx4 v[52:55], v[8:9], off nt
	v_lshl_add_u64 v[8:9], v[8:9], 0, s[10:11]
	global_load_dwordx4 v[56:59], v[8:9], off nt
	v_lshl_add_u64 v[8:9], v[8:9], 0, s[10:11]
	global_load_dwordx4 v[60:63], v[8:9], off nt
	v_lshl_add_u64 v[8:9], v[8:9], 0, s[10:11]
	global_load_dwordx4 v[64:67], v[8:9], off nt
	v_lshl_add_u64 v[8:9], v[8:9], 0, s[10:11]
	global_load_dwordx4 v[68:71], v[8:9], off nt
	v_lshl_add_u64 v[8:9], v[8:9], 0, s[10:11]
	global_load_dwordx4 v[72:75], v[8:9], off nt
	v_lshl_add_u64 v[8:9], v[8:9], 0, s[10:11]
	global_load_dwordx4 v[76:79], v[8:9], off nt
	v_lshl_add_u64 v[8:9], v[8:9], 0, s[10:11]
	s_waitcnt vmcnt(16)
	v_mul_f32_e32 v96, 0xbfb8aa3b, v80
	v_mul_f32_e32 v97, 0xbfb8aa3b, v81
	v_mul_f32_e32 v98, 0xbfb8aa3b, v82
	v_mul_f32_e32 v99, 0xbfb8aa3b, v83
	v_mul_f32_e32 v100, 0xbfb8aa3b, v84
	v_mul_f32_e32 v101, 0xbfb8aa3b, v85
	v_mul_f32_e32 v102, 0xbfb8aa3b, v86
	v_mul_f32_e32 v103, 0xbfb8aa3b, v87
	v_mul_f32_e32 v104, 0xbfb8aa3b, v88
	v_mul_f32_e32 v105, 0xbfb8aa3b, v89
	v_mul_f32_e32 v106, 0xbfb8aa3b, v90
	v_mul_f32_e32 v107, 0xbfb8aa3b, v91
	v_mul_f32_e32 v108, 0xbfb8aa3b, v92
	v_mul_f32_e32 v109, 0xbfb8aa3b, v93
	v_mul_f32_e32 v110, 0xbfb8aa3b, v94
	v_mul_f32_e32 v111, 0xbfb8aa3b, v95
	v_exp_f32_e32 v96, v96
	v_exp_f32_e32 v97, v97
	v_exp_f32_e32 v98, v98
	v_exp_f32_e32 v99, v99
	v_exp_f32_e32 v100, v100
	v_exp_f32_e32 v101, v101
	v_exp_f32_e32 v102, v102
	v_exp_f32_e32 v103, v103
	v_exp_f32_e32 v104, v104
	v_exp_f32_e32 v105, v105
	v_exp_f32_e32 v106, v106
	v_exp_f32_e32 v107, v107
	v_exp_f32_e32 v108, v108
	v_exp_f32_e32 v109, v109
	v_exp_f32_e32 v110, v110
	v_exp_f32_e32 v111, v111
	v_add_f32_e32 v96, 1.0, v96
	v_add_f32_e32 v97, 1.0, v97
	v_add_f32_e32 v98, 1.0, v98
	v_add_f32_e32 v99, 1.0, v99
	v_add_f32_e32 v100, 1.0, v100
	v_add_f32_e32 v101, 1.0, v101
	v_add_f32_e32 v102, 1.0, v102
	v_add_f32_e32 v103, 1.0, v103
	v_add_f32_e32 v104, 1.0, v104
	v_add_f32_e32 v105, 1.0, v105
	v_add_f32_e32 v106, 1.0, v106
	v_add_f32_e32 v107, 1.0, v107
	v_add_f32_e32 v108, 1.0, v108
	v_add_f32_e32 v109, 1.0, v109
	v_add_f32_e32 v110, 1.0, v110
	v_add_f32_e32 v111, 1.0, v111
	v_rcp_f32_e32 v96, v96
	v_rcp_f32_e32 v97, v97
	v_rcp_f32_e32 v98, v98
	v_rcp_f32_e32 v99, v99
	v_rcp_f32_e32 v100, v100
	v_rcp_f32_e32 v101, v101
	v_rcp_f32_e32 v102, v102
	v_rcp_f32_e32 v103, v103
	v_rcp_f32_e32 v104, v104
	v_rcp_f32_e32 v105, v105
	v_rcp_f32_e32 v106, v106
	v_rcp_f32_e32 v107, v107
	v_rcp_f32_e32 v108, v108
	v_rcp_f32_e32 v109, v109
	v_rcp_f32_e32 v110, v110
	v_rcp_f32_e32 v111, v111
	v_mul_f32_e32 v80, v80, v96
	v_mul_f32_e32 v81, v81, v97
	v_mul_f32_e32 v82, v82, v98
	v_mul_f32_e32 v83, v83, v99
	v_mul_f32_e32 v84, v84, v100
	v_mul_f32_e32 v85, v85, v101
	v_mul_f32_e32 v86, v86, v102
	v_mul_f32_e32 v87, v87, v103
	v_mul_f32_e32 v88, v88, v104
	v_mul_f32_e32 v89, v89, v105
	v_mul_f32_e32 v90, v90, v106
	v_mul_f32_e32 v91, v91, v107
	v_mul_f32_e32 v92, v92, v108
	v_mul_f32_e32 v93, v93, v109
	v_mul_f32_e32 v94, v94, v110
	v_mul_f32_e32 v95, v95, v111
	s_waitcnt vmcnt(15)
	v_pk_fma_f32 v[2:3], v[16:17], v[80:81], v[2:3] op_sel_hi:[1,0,1]
	v_pk_fma_f32 v[4:5], v[18:19], v[80:81], v[4:5] op_sel_hi:[1,0,1]
	s_waitcnt vmcnt(14)
	v_pk_fma_f32 v[2:3], v[20:21], v[80:81], v[2:3] op_sel:[0,1,0] op_sel_hi:[1,1,1]
	v_pk_fma_f32 v[4:5], v[22:23], v[80:81], v[4:5] op_sel:[0,1,0] op_sel_hi:[1,1,1]
	s_waitcnt vmcnt(13)
	v_pk_fma_f32 v[2:3], v[24:25], v[82:83], v[2:3] op_sel_hi:[1,0,1]
	v_pk_fma_f32 v[4:5], v[26:27], v[82:83], v[4:5] op_sel_hi:[1,0,1]
	s_waitcnt vmcnt(12)
	v_pk_fma_f32 v[2:3], v[28:29], v[82:83], v[2:3] op_sel:[0,1,0] op_sel_hi:[1,1,1]
	v_pk_fma_f32 v[4:5], v[30:31], v[82:83], v[4:5] op_sel:[0,1,0] op_sel_hi:[1,1,1]
	s_waitcnt vmcnt(11)
	v_pk_fma_f32 v[2:3], v[32:33], v[84:85], v[2:3] op_sel_hi:[1,0,1]
	v_pk_fma_f32 v[4:5], v[34:35], v[84:85], v[4:5] op_sel_hi:[1,0,1]
	s_waitcnt vmcnt(10)
	v_pk_fma_f32 v[2:3], v[36:37], v[84:85], v[2:3] op_sel:[0,1,0] op_sel_hi:[1,1,1]
	v_pk_fma_f32 v[4:5], v[38:39], v[84:85], v[4:5] op_sel:[0,1,0] op_sel_hi:[1,1,1]
	s_waitcnt vmcnt(9)
	v_pk_fma_f32 v[2:3], v[40:41], v[86:87], v[2:3] op_sel_hi:[1,0,1]
	v_pk_fma_f32 v[4:5], v[42:43], v[86:87], v[4:5] op_sel_hi:[1,0,1]
	s_waitcnt vmcnt(8)
	v_pk_fma_f32 v[2:3], v[44:45], v[86:87], v[2:3] op_sel:[0,1,0] op_sel_hi:[1,1,1]
	v_pk_fma_f32 v[4:5], v[46:47], v[86:87], v[4:5] op_sel:[0,1,0] op_sel_hi:[1,1,1]
	s_waitcnt vmcnt(7)
	v_pk_fma_f32 v[2:3], v[48:49], v[88:89], v[2:3] op_sel_hi:[1,0,1]
	v_pk_fma_f32 v[4:5], v[50:51], v[88:89], v[4:5] op_sel_hi:[1,0,1]
	s_waitcnt vmcnt(6)
	v_pk_fma_f32 v[2:3], v[52:53], v[88:89], v[2:3] op_sel:[0,1,0] op_sel_hi:[1,1,1]
	v_pk_fma_f32 v[4:5], v[54:55], v[88:89], v[4:5] op_sel:[0,1,0] op_sel_hi:[1,1,1]
	s_waitcnt vmcnt(5)
	v_pk_fma_f32 v[2:3], v[56:57], v[90:91], v[2:3] op_sel_hi:[1,0,1]
	v_pk_fma_f32 v[4:5], v[58:59], v[90:91], v[4:5] op_sel_hi:[1,0,1]
	s_waitcnt vmcnt(4)
	v_pk_fma_f32 v[2:3], v[60:61], v[90:91], v[2:3] op_sel:[0,1,0] op_sel_hi:[1,1,1]
	v_pk_fma_f32 v[4:5], v[62:63], v[90:91], v[4:5] op_sel:[0,1,0] op_sel_hi:[1,1,1]
	s_waitcnt vmcnt(3)
	v_pk_fma_f32 v[2:3], v[64:65], v[92:93], v[2:3] op_sel_hi:[1,0,1]
	v_pk_fma_f32 v[4:5], v[66:67], v[92:93], v[4:5] op_sel_hi:[1,0,1]
	s_waitcnt vmcnt(2)
	v_pk_fma_f32 v[2:3], v[68:69], v[92:93], v[2:3] op_sel:[0,1,0] op_sel_hi:[1,1,1]
	v_pk_fma_f32 v[4:5], v[70:71], v[92:93], v[4:5] op_sel:[0,1,0] op_sel_hi:[1,1,1]
	s_waitcnt vmcnt(1)
	v_pk_fma_f32 v[2:3], v[72:73], v[94:95], v[2:3] op_sel_hi:[1,0,1]
	v_pk_fma_f32 v[4:5], v[74:75], v[94:95], v[4:5] op_sel_hi:[1,0,1]
	s_waitcnt vmcnt(0)
	v_pk_fma_f32 v[2:3], v[76:77], v[94:95], v[2:3] op_sel:[0,1,0] op_sel_hi:[1,1,1]
	v_pk_fma_f32 v[4:5], v[78:79], v[94:95], v[4:5] op_sel:[0,1,0] op_sel_hi:[1,1,1]
	s_sub_u32 s8, s8, 1
	s_cmp_lg_u32 s8, 0
	s_cbranch_scc1 .Lg5_loop
	v_lshrrev_b32_e32 v1, 4, v147
	v_lshl_add_u32 v1, s20, 2, v1
	v_and_b32_e32 v6, 15, v147
	v_lshlrev_b32_e32 v6, 4, v6
	v_lshl_add_u32 v1, v1, 8, v6
	v_add_u32_e32 v1, 0x21000, v1
	ds_write_b128 v1, v[2:5]
	s_waitcnt lgkmcnt(0)
	s_barrier
	s_cmp_lg_u32 s20, 0
	s_cbranch_scc1 .Lg5_skip
	v_lshlrev_b32_e32 v1, 2, v147
	v_readlane_b32 s4, v241, 11
	v_readlane_b32 s5, v241, 12
	s_nop 3
	s_add_u32 s4, s4, s1
	s_addc_u32 s5, s5, 0
	global_load_dword v2, v1, s[4:5]
	v_add_u32_e32 v3, 0x21000, v1
	ds_read_b32 v16, v3 offset:0
	ds_read_b32 v17, v3 offset:256
	ds_read_b32 v18, v3 offset:512
	ds_read_b32 v19, v3 offset:768
	ds_read_b32 v20, v3 offset:1024
	ds_read_b32 v21, v3 offset:1280
	ds_read_b32 v22, v3 offset:1536
	ds_read_b32 v23, v3 offset:1792
	ds_read_b32 v24, v3 offset:2048
	ds_read_b32 v25, v3 offset:2304
	ds_read_b32 v26, v3 offset:2560
	ds_read_b32 v27, v3 offset:2816
	ds_read_b32 v28, v3 offset:3072
	ds_read_b32 v29, v3 offset:3328
	ds_read_b32 v30, v3 offset:3584
	ds_read_b32 v31, v3 offset:3840
	ds_read_b32 v32, v3 offset:4096
	ds_read_b32 v33, v3 offset:4352
	ds_read_b32 v34, v3 offset:4608
	ds_read_b32 v35, v3 offset:4864
	ds_read_b32 v36, v3 offset:5120
	ds_read_b32 v37, v3 offset:5376
	ds_read_b32 v38, v3 offset:5632
	ds_read_b32 v39, v3 offset:5888
	ds_read_b32 v40, v3 offset:6144
	ds_read_b32 v41, v3 offset:6400
	ds_read_b32 v42, v3 offset:6656
	ds_read_b32 v43, v3 offset:6912
	ds_read_b32 v44, v3 offset:7168
	ds_read_b32 v45, v3 offset:7424
	ds_read_b32 v46, v3 offset:7680
	ds_read_b32 v47, v3 offset:7936
	s_waitcnt vmcnt(0) lgkmcnt(0)
	v_add_f32_e32 v2, v2, v16
	v_add_f32_e32 v2, v2, v17
	v_add_f32_e32 v2, v2, v18
	v_add_f32_e32 v2, v2, v19
	v_add_f32_e32 v2, v2, v20
	v_add_f32_e32 v2, v2, v21
	v_add_f32_e32 v2, v2, v22
	v_add_f32_e32 v2, v2, v23
	v_add_f32_e32 v2, v2, v24
	v_add_f32_e32 v2, v2, v25
	v_add_f32_e32 v2, v2, v26
	v_add_f32_e32 v2, v2, v27
	v_add_f32_e32 v2, v2, v28
	v_add_f32_e32 v2, v2, v29
	v_add_f32_e32 v2, v2, v30
	v_add_f32_e32 v2, v2, v31
	v_add_f32_e32 v2, v2, v32
	v_add_f32_e32 v2, v2, v33
	v_add_f32_e32 v2, v2, v34
	v_add_f32_e32 v2, v2, v35
	v_add_f32_e32 v2, v2, v36
	v_add_f32_e32 v2, v2, v37
	v_add_f32_e32 v2, v2, v38
	v_add_f32_e32 v2, v2, v39
	v_add_f32_e32 v2, v2, v40
	v_add_f32_e32 v2, v2, v41
	v_add_f32_e32 v2, v2, v42
	v_add_f32_e32 v2, v2, v43
	v_add_f32_e32 v2, v2, v44
	v_add_f32_e32 v2, v2, v45
	v_add_f32_e32 v2, v2, v46
	v_add_f32_e32 v2, v2, v47
	s_add_u32 s4, s94, s1
	s_addc_u32 s5, s95, 0
	s_add_u32 s4, s4, 0x300000
	s_addc_u32 s5, s5, 0
	global_store_dword v1, v2, s[4:5]

	.amdhsa_kernel _Z10fwd_kernel4Args
		.amdhsa_group_segment_fixed_size 256
		.amdhsa_private_segment_fixed_size 0
		.amdhsa_kernarg_size 472
		.amdhsa_user_sgpr_count 2
		.amdhsa_user_sgpr_dispatch_ptr 0
		.amdhsa_user_sgpr_queue_ptr 0
		.amdhsa_user_sgpr_kernarg_segment_ptr 1
		.amdhsa_user_sgpr_dispatch_id 0
		.amdhsa_user_sgpr_kernarg_preload_length 0
		.amdhsa_user_sgpr_kernarg_preload_offset 0
		.amdhsa_user_sgpr_private_segment_size 0
		.amdhsa_uses_dynamic_stack 0
		.amdhsa_enable_private_segment 0
		.amdhsa_system_sgpr_workgroup_id_x 1
		.amdhsa_system_sgpr_workgroup_id_y 0
		.amdhsa_system_sgpr_workgroup_id_z 0
		.amdhsa_system_sgpr_workgroup_info 0
		.amdhsa_system_vgpr_workitem_id 2
		.amdhsa_next_free_vgpr 242
		.amdhsa_next_free_sgpr 102
		.amdhsa_accum_offset 244
		.amdhsa_reserve_vcc 1
		.amdhsa_float_round_mode_32 0
		.amdhsa_float_round_mode_16_64 0
		.amdhsa_float_denorm_mode_32 3
		.amdhsa_float_denorm_mode_16_64 3
		.amdhsa_dx10_clamp 1
		.amdhsa_ieee_mode 1
		.amdhsa_fp16_overflow 0
		.amdhsa_tg_split 0
		.amdhsa_exception_fp_ieee_invalid_op 0
		.amdhsa_exception_fp_denorm_src 0
		.amdhsa_exception_fp_ieee_div_zero 0
		.amdhsa_exception_fp_ieee_overflow 0
		.amdhsa_exception_fp_ieee_underflow 0
		.amdhsa_exception_fp_ieee_inexact 0
		.amdhsa_exception_int_div_zero 0
	.end_amdhsa_kernel

amdhsa.kernels:
  - .agpr_count:     0
    .args:
      - .offset:         0
        .size:           216
        .value_kind:     by_value
      - .offset:         216
        .size:           4
        .value_kind:     hidden_block_count_x
      - .offset:         220
        .size:           4
        .value_kind:     hidden_block_count_y
      - .offset:         224
        .size:           4
        .value_kind:     hidden_block_count_z
      - .offset:         228
        .size:           2
        .value_kind:     hidden_group_size_x
      - .offset:         230
        .size:           2
        .value_kind:     hidden_group_size_y
      - .offset:         232
        .size:           2
        .value_kind:     hidden_group_size_z
      - .offset:         234
        .size:           2
        .value_kind:     hidden_remainder_x
      - .offset:         236
        .size:           2
        .value_kind:     hidden_remainder_y
      - .offset:         238
        .size:           2
        .value_kind:     hidden_remainder_z
      - .offset:         256
        .size:           8
        .value_kind:     hidden_global_offset_x
      - .offset:         264
        .size:           8
        .value_kind:     hidden_global_offset_y
      - .offset:         272
        .size:           8
        .value_kind:     hidden_global_offset_z
      - .offset:         280
        .size:           2
        .value_kind:     hidden_grid_dims
      - .offset:         304
        .size:           8
        .value_kind:     hidden_multigrid_sync_arg
      - .offset:         336
        .size:           4
        .value_kind:     hidden_dynamic_lds_size
    .group_segment_fixed_size: 256
    .kernarg_segment_align: 8
    .kernarg_segment_size: 472
    .language:       OpenCL C
    .language_version:
      - 2
      - 0
    .max_flat_workgroup_size: 512
    .name:           _Z10fwd_kernel4Args
    .private_segment_fixed_size: 0
    .sgpr_count:     108
    .sgpr_spill_count: 103
    .symbol:         _Z10fwd_kernel4Args.kd
    .uniform_work_group_size: 1
    .uses_dynamic_stack: false
    .vgpr_count:     242
    .vgpr_spill_count: 0
    .wavefront_size: 64
